# attention tile loop: next tile's K/V global loads issued before the per-tile workgroup barrier instead of after it
# speedup vs baseline: 1.0110x; 1.0001x over previous
; #define LAS __attribute__((address_space(3)))
; __device__ __forceinline__ void attn_unit(LAS unsigned char* lds, const bf16_t* Q, const bf16_t* Kb, const bf16_t* Vb, bf16_t* O, const float* sink,
;                                           int qrow0, int kvh, int crow0, int lrow0, int jlo, int jhi, int qpos0, const int wave_s) {
;     ...
;     for (int ti = 0; ti < ntile; ++ti) {
;         asm volatile(".p2align 4\n\ts_nop 0" ::: "memory");
;         LAS unsigned char* kb = lds + ATT_K + (ti & 1) * 64 * KSTR; LAS unsigned char* vb = lds + ATT_V + (ti & 1) * 64 * VSTR;
;         *(LAS u32x4*)(kb + skey * KSTR + sch * 16) = kreg; *(LAS u32x4*)(vb + skey * VSTR + sch * 16) = vreg;
;         __syncthreads();
;         if (ti + 1 < ntile) { const int tn = ti + 1; const int rb = tn < 4 ? crow0 + 64 * tn : lrow0 + 64 * (jlo + tn - 4);
;             kreg = *(const u32x4*)(Kb + (size_t)(rb + skey) * 256 + gcol); vreg = *(const u32x4*)(Vb + (size_t)(rb + skey) * 256 + gcol); }
.LBB0_347:
	s_and_b32 s8, s2, 64
	s_mul_i32 s9, s8, 0x90
	s_add_i32 s34, s9, 0
	s_mul_i32 s8, s8, 48
	s_add_i32 s31, s34, s8
	s_add_i32 s29, s30, 1
	.p2align 4
	s_nop 0
	s_cmp_ge_u32 s29, s21
	v_add3_u32 v64, s34, v193, v192
	s_cselect_b64 s[8:9], -1, 0
	s_waitcnt vmcnt(0)
	ds_write_b128 v64, v[132:135]
	v_add3_u32 v64, s31, v194, v192
	s_and_b64 vcc, exec, s[8:9]
	ds_write_b128 v64, v[128:131] offset:18432
	s_waitcnt lgkmcnt(0)
	s_cbranch_vccnz .LBB0_353
	s_cmp_gt_u32 s30, 2
	s_mov_b64 s[12:13], -1
	s_cbranch_scc0 .LBB0_350
	s_add_i32 s12, s29, s20
	s_lshl_b32 s12, s12, 6
	s_add_i32 s35, s26, s12
	s_mov_b64 s[12:13], 0

; #define LAS __attribute__((address_space(3)))
; __device__ __forceinline__ void attn_unit(LAS unsigned char* lds, const bf16_t* Q, const bf16_t* Kb, const bf16_t* Vb, bf16_t* O, const float* sink,
;                                           int qrow0, int kvh, int crow0, int lrow0, int jlo, int jhi, int qpos0, const int wave_s) {
;     ...
;         __syncthreads();
;         if (ti + 1 < ntile) { const int tn = ti + 1; const int rb = tn < 4 ? crow0 + 64 * tn : lrow0 + 64 * (jlo + tn - 4);
;             kreg = *(const u32x4*)(Kb + (size_t)(rb + skey) * 256 + gcol); vreg = *(const u32x4*)(Vb + (size_t)(rb + skey) * 256 + gcol); }
;         const int jl = ti < 4 ? -1 : jlo + ti - 4;
;         const bool masked = (jl == 0) || (jl == 4);
;         const int kp0 = qpos0 - 128 + 64 * jl;
;         bf16x8 Kf[2][4];
; #pragma unroll
;         for (int kt = 0; kt < 2; ++kt)
; #pragma unroll
;             for (int ks = 0; ks < 4; ++ks) Kf[kt][ks] = *(const LAS bf16x8*)(kb + (32 * kt + l31) * KSTR + (16 * ks + 8 * h) * 2);
; #pragma unroll
;         for (int qs = 0; qs < 2; ++qs) {
;             f32x16 S[2];
; #pragma unroll
;             for (int kt = 0; kt < 2; ++kt) {
; #pragma unroll
;                 for (int r = 0; r < 16; ++r) S[kt][r] = 0.f;
; #pragma unroll
;                 for (int ks = 0; ks < 4; ++ks) S[kt] = __builtin_amdgcn_mfma_f32_32x32x16_bf16(Kf[kt][ks], Qf[qs][ks], S[kt], 0, 0, 0);
;             }
;             if (masked) {
;                 const int qp = qpos0 + 32 * qs + l31;
; #pragma unroll
;                 for (int kt = 0; kt < 2; ++kt)
; #pragma unroll
;                     for (int r = 0; r < 16; ++r) { const int dlt = kp0 + 32 * kt + (r & 3) + 8 * (r >> 2) + 4 * h - qp; if (dlt > 128 || dlt < -128) S[kt][r] = -INFINITY; }
;             }
.LBB0_353:
	s_barrier
	v_add3_u32 v164, s34, v176, v196
	ds_read_b128 v[140:143], v164
	ds_read_b128 v[136:139], v164 offset:32
	ds_read_b128 v[148:151], v164 offset:64
	ds_read_b128 v[144:147], v164 offset:96
	ds_read_b128 v[156:159], v164 offset:4608
	ds_read_b128 v[152:155], v164 offset:4640
	ds_read_b128 v[160:163], v164 offset:4672
	s_waitcnt lgkmcnt(6)
	v_mfma_f32_32x32x16_bf16 v[80:95], v[140:143], v[96:99], 0
	ds_read_b128 v[164:167], v164 offset:4704
	s_add_i32 s12, s27, s30
	s_cmp_gt_u32 s30, 3
	s_cselect_b32 s14, s12, -1
	s_and_b32 s15, s14, -5
	s_cmp_eq_u32 s15, 0
	s_cselect_b64 s[12:13], -1, 0
	s_waitcnt lgkmcnt(3)
	v_mfma_f32_32x32x16_bf16 v[64:79], v[156:159], v[96:99], 0
	s_cmp_lg_u32 s15, 0
	v_lshl_add_u32 v204, s14, 6, v199
	v_mfma_f32_32x32x16_bf16 v[80:95], v[136:139], v[100:103], v[80:95]
	s_waitcnt lgkmcnt(2)
	v_mfma_f32_32x32x16_bf16 v[64:79], v[152:155], v[100:103], v[64:79]
	v_mfma_f32_32x32x16_bf16 v[80:95], v[148:151], v[104:107], v[80:95]
	s_waitcnt lgkmcnt(1)
	v_mfma_f32_32x32x16_bf16 v[64:79], v[160:163], v[104:107], v[64:79]
	v_mfma_f32_32x32x16_bf16 v[80:95], v[144:147], v[108:111], v[80:95]
	s_waitcnt lgkmcnt(0)
	v_mfma_f32_32x32x16_bf16 v[64:79], v[164:167], v[108:111], v[64:79]
	s_cbranch_scc1 .LBB0_355
	v_cmp_gt_u32_e32 vcc, s52, v204
	v_add_u32_e32 v178, 1, v204
	s_nop 6
	v_cndmask_b32_e32 v80, v80, v220, vcc
	v_cmp_lt_u32_e32 vcc, s89, v178
	v_add_u32_e32 v178, 2, v204
	s_nop 0
	v_cndmask_b32_e32 v81, v220, v81, vcc
	v_cmp_lt_u32_e32 vcc, s89, v178
	v_add_u32_e32 v178, 3, v204
	s_nop 0
	v_cndmask_b32_e32 v82, v220, v82, vcc
	v_cmp_lt_u32_e32 vcc, s89, v178
	v_add_u32_e32 v178, 8, v204
	s_nop 0
	v_cndmask_b32_e32 v83, v220, v83, vcc
	v_cmp_lt_u32_e32 vcc, s89, v178
	v_add_u32_e32 v178, 9, v204
	s_nop 0
	v_cndmask_b32_e32 v84, v220, v84, vcc
	v_cmp_lt_u32_e32 vcc, s89, v178
	v_add_u32_e32 v178, 10, v204
	s_nop 0
	v_cndmask_b32_e32 v85, v220, v85, vcc
	v_cmp_lt_u32_e32 vcc, s89, v178
	v_add_u32_e32 v178, 11, v204
	s_nop 0
	v_cndmask_b32_e32 v86, v220, v86, vcc
	v_cmp_lt_u32_e32 vcc, s89, v178
	v_add_u32_e32 v178, 16, v204
	s_nop 0
	v_cndmask_b32_e32 v87, v220, v87, vcc
	v_cmp_lt_u32_e32 vcc, s89, v178
	v_add_u32_e32 v178, 17, v204
	s_nop 0
	v_cndmask_b32_e32 v88, v220, v88, vcc
	v_cmp_lt_u32_e32 vcc, s89, v178
	v_add_u32_e32 v178, 18, v204
	s_nop 0
	v_cndmask_b32_e32 v89, v220, v89, vcc
	v_cmp_lt_u32_e32 vcc, s89, v178
	v_add_u32_e32 v178, 19, v204
	s_nop 0
	v_cndmask_b32_e32 v90, v220, v90, vcc
	v_cmp_lt_u32_e32 vcc, s89, v178
	v_add_u32_e32 v178, 24, v204
	s_nop 0
	v_cndmask_b32_e32 v91, v220, v91, vcc
	v_cmp_lt_u32_e32 vcc, s89, v178
	v_add_u32_e32 v178, 25, v204
	s_nop 0
	v_cndmask_b32_e32 v92, v220, v92, vcc
	v_cmp_lt_u32_e32 vcc, s89, v178
	v_add_u32_e32 v178, 26, v204
	s_nop 0
	v_cndmask_b32_e32 v93, v220, v93, vcc
	v_cmp_lt_u32_e32 vcc, s89, v178
	v_add_u32_e32 v178, 27, v204
	s_nop 0
	v_cndmask_b32_e32 v94, v220, v94, vcc
	v_cmp_lt_u32_e32 vcc, s89, v178
	v_add_u32_e32 v178, 32, v204
	s_nop 0
	v_cndmask_b32_e32 v95, v220, v95, vcc
	v_cmp_lt_u32_e32 vcc, s89, v178
	v_add_u32_e32 v178, 33, v204
	s_nop 0
	v_cndmask_b32_e32 v64, v220, v64, vcc
	v_cmp_lt_u32_e32 vcc, s89, v178
	v_add_u32_e32 v178, 34, v204
	s_nop 0
	v_cndmask_b32_e32 v65, v220, v65, vcc
	v_cmp_lt_u32_e32 vcc, s89, v178
	v_add_u32_e32 v178, 35, v204
	s_nop 0
	v_cndmask_b32_e32 v66, v220, v66, vcc
	v_cmp_lt_u32_e32 vcc, s89, v178
	v_add_u32_e32 v178, 40, v204
	s_nop 0
	v_cndmask_b32_e32 v67, v220, v67, vcc
	v_cmp_lt_u32_e32 vcc, s89, v178
	v_add_u32_e32 v178, 41, v204
	s_nop 0
	v_cndmask_b32_e32 v68, v220, v68, vcc
	v_cmp_lt_u32_e32 vcc, s89, v178
	v_add_u32_e32 v178, 42, v204
	s_nop 0
	v_cndmask_b32_e32 v69, v220, v69, vcc
	v_cmp_lt_u32_e32 vcc, s89, v178
	v_add_u32_e32 v178, 43, v204
	s_nop 0
	v_cndmask_b32_e32 v70, v220, v70, vcc
	v_cmp_lt_u32_e32 vcc, s89, v178
	v_add_u32_e32 v178, 48, v204
	s_nop 0
	v_cndmask_b32_e32 v71, v220, v71, vcc
	v_cmp_lt_u32_e32 vcc, s89, v178
	v_add_u32_e32 v178, 49, v204
	s_nop 0
	v_cndmask_b32_e32 v72, v220, v72, vcc
	v_cmp_lt_u32_e32 vcc, s89, v178
	v_add_u32_e32 v178, 50, v204
	s_nop 0
	v_cndmask_b32_e32 v73, v220, v73, vcc
	v_cmp_lt_u32_e32 vcc, s89, v178
	v_add_u32_e32 v178, 51, v204
	s_nop 0
	v_cndmask_b32_e32 v74, v220, v74, vcc
	v_cmp_lt_u32_e32 vcc, s89, v178
	v_add_u32_e32 v178, 56, v204
	s_nop 0
	v_cndmask_b32_e32 v75, v220, v75, vcc
	v_cmp_lt_u32_e32 vcc, s89, v178
	v_add_u32_e32 v178, 57, v204
	s_nop 0
	v_cndmask_b32_e32 v76, v220, v76, vcc
	v_cmp_lt_u32_e32 vcc, s89, v178
	v_add_u32_e32 v178, 58, v204
	s_nop 0
	v_cndmask_b32_e32 v77, v220, v77, vcc
	v_cmp_lt_u32_e32 vcc, s89, v178
	v_add_u32_e32 v178, 59, v204
	s_nop 0
	v_cndmask_b32_e32 v78, v220, v78, vcc
	v_cmp_lt_u32_e32 vcc, s89, v178
	s_nop 1
	v_cndmask_b32_e32 v79, v220, v79, vcc
